# v33 + FoX main loop: three of the eight per-tile bias-table LDS reads hoisted to the loop top into free VGPRs (first half-trip)
# speedup vs baseline: 1.0018x; 1.0018x over previous
.LBB0_787:
	ds_read_b128 v[236:239], v196
	ds_read_b128 v[240:243], v196 offset:32
	ds_read_b128 v[244:247], v196 offset:64
	v_add_u32_e32 v180, s10, v229
	ds_read_b64_tr_b16 v[176:177], v180 offset:24576
	ds_read_b64_tr_b16 v[178:179], v180 offset:25088
	v_add_f32_e32 v80, v64, v65
	v_add_f32_e32 v80, v66, v80
	v_add_f32_e32 v80, v67, v80
	v_add_f32_e32 v80, v68, v80
	v_add_f32_e32 v96, v69, v80
	v_mfma_f32_32x32x16_bf16 v[80:95], v[172:175], v[128:131], v[32:47]
	v_cvt_pk_bf16_f32 v140, v64, v65
	v_cvt_pk_bf16_f32 v141, v66, v67
	ds_read_b64_tr_b16 v[172:173], v180 offset:28672
	ds_read_b64_tr_b16 v[174:175], v180 offset:29184
	v_add_f32_e32 v64, v70, v96
	v_add_f32_e32 v64, v71, v64
	v_add_f32_e32 v64, v72, v64
	v_add_f32_e32 v64, v73, v64
	v_cvt_pk_bf16_f32 v142, v68, v69
	v_cvt_pk_bf16_f32 v143, v70, v71
	v_mfma_f32_32x32x16_bf16 v[96:111], v[168:171], v[128:131], v[32:47]
	ds_read_b64_tr_b16 v[168:169], v180 offset:25600
	ds_read_b64_tr_b16 v[170:171], v180 offset:26112
	v_mfma_f32_32x32x16_bf16 v[80:95], v[164:167], v[120:123], v[80:95]
	v_add_f32_e32 v64, v74, v64
	v_add_f32_e32 v64, v75, v64
	v_add_f32_e32 v64, v76, v64
	v_add_f32_e32 v64, v77, v64
	v_cvt_pk_bf16_f32 v136, v72, v73
	v_cvt_pk_bf16_f32 v137, v74, v75
	ds_read_b64_tr_b16 v[164:165], v180 offset:29696
	ds_read_b64_tr_b16 v[166:167], v180 offset:30208
	v_add_f32_e32 v64, v78, v64
	v_add_f32_e32 v64, v79, v64
	v_add_f32_e32 v64, v48, v64
	v_add_f32_e32 v64, v49, v64
	v_cvt_pk_bf16_f32 v138, v76, v77
	v_cvt_pk_bf16_f32 v139, v78, v79
	v_mfma_f32_32x32x16_bf16 v[96:111], v[160:163], v[120:123], v[96:111]
	ds_read_b64_tr_b16 v[160:161], v180 offset:26624
	ds_read_b64_tr_b16 v[162:163], v180 offset:27136
	v_mfma_f32_32x32x16_bf16 v[80:95], v[156:159], v[116:119], v[80:95]
	v_add_f32_e32 v64, v50, v64
	v_add_f32_e32 v64, v51, v64
	v_add_f32_e32 v64, v52, v64
	v_add_f32_e32 v64, v53, v64
	v_cvt_pk_bf16_f32 v132, v48, v49
	v_cvt_pk_bf16_f32 v133, v50, v51
	ds_read_b64_tr_b16 v[156:157], v180 offset:30720
	ds_read_b64_tr_b16 v[158:159], v180 offset:31232
	v_add_f32_e32 v48, v54, v64
	v_add_f32_e32 v48, v55, v48
	v_add_f32_e32 v48, v56, v48
	v_add_f32_e32 v48, v57, v48
	v_cvt_pk_bf16_f32 v134, v52, v53
	v_cvt_pk_bf16_f32 v135, v54, v55
	v_mfma_f32_32x32x16_bf16 v[96:111], v[152:155], v[116:119], v[96:111]
	ds_read_b64_tr_b16 v[152:153], v180 offset:27648
	ds_read_b64_tr_b16 v[154:155], v180 offset:28160
	v_mfma_f32_32x32x16_bf16 v[80:95], v[148:151], v[112:115], v[80:95]
	v_add_f32_e32 v48, v58, v48
	v_add_f32_e32 v48, v59, v48
	v_add_f32_e32 v48, v60, v48
	v_add_f32_e32 v48, v61, v48
	v_cvt_pk_bf16_f32 v124, v56, v57
	v_cvt_pk_bf16_f32 v125, v58, v59
	ds_read_b64_tr_b16 v[148:149], v180 offset:31744
	ds_read_b64_tr_b16 v[150:151], v180 offset:32256
	v_add_f32_e32 v48, v62, v48
	v_add_f32_e32 v48, v63, v48
	v_add_f32_e32 v180, 0, v48
	v_cvt_pk_bf16_f32 v126, v60, v61
	v_cvt_pk_bf16_f32 v127, v62, v63
	v_mfma_f32_32x32x16_bf16 v[96:111], v[144:147], v[112:115], v[96:111]
	s_waitcnt lgkmcnt(8)
	ds_read_b128 v[76:79], v196 offset:96
	ds_read_b128 v[52:55], v196 offset:160
	ds_read_b128 v[56:59], v196 offset:192
	ds_read_b128 v[60:63], v196 offset:224
	v_lshl_add_u64 v[48:49], v[194:195], 0, s[24:25]
	s_add_i32 s0, s36, s65
	s_mov_b32 m0, s0
	s_nop 0
	global_load_lds_dwordx4 v[48:49], off
	v_lshl_add_u64 v[48:49], v[192:193], 0, s[24:25]
	s_add_i32 s0, s1, s68
	s_mov_b32 m0, s0
	s_nop 0
	global_load_lds_dwordx4 v[48:49], off
	ds_read_b128 v[48:51], v196 offset:128
	s_waitcnt lgkmcnt(4)
	v_add_f32_e32 v64, v80, v236
	v_add_f32_e32 v65, v81, v237
	v_add_f32_e32 v66, v82, v238
	v_add_f32_e32 v67, v83, v239
	v_add_f32_e32 v68, v84, v240
	v_add_f32_e32 v69, v85, v241
	v_add_f32_e32 v70, v86, v242
	v_add_f32_e32 v71, v87, v243
	v_add_f32_e32 v72, v88, v244
	v_add_f32_e32 v73, v89, v245
	v_add_f32_e32 v74, v90, v246
	v_add_f32_e32 v75, v91, v247
	v_add_f32_e32 v76, v92, v76
	v_add_f32_e32 v77, v93, v77
	v_add_f32_e32 v78, v94, v78
	v_add_f32_e32 v79, v95, v79
	s_waitcnt lgkmcnt(1)
	v_add_f32_e32 v52, v100, v52
	v_add_f32_e32 v53, v101, v53
	v_add_f32_e32 v54, v102, v54
	v_add_f32_e32 v55, v103, v55
	v_add_f32_e32 v56, v104, v56
	v_add_f32_e32 v57, v105, v57
	v_add_f32_e32 v58, v106, v58
	v_add_f32_e32 v59, v107, v59
	v_add_f32_e32 v60, v108, v60
	v_add_f32_e32 v61, v109, v61
	v_add_f32_e32 v62, v110, v62
	v_add_f32_e32 v63, v111, v63
	s_waitcnt lgkmcnt(0)
	v_add_f32_e32 v48, v96, v48
	v_add_f32_e32 v49, v97, v49
	v_add_f32_e32 v50, v98, v50
	v_add_f32_e32 v51, v99, v51
	v_max_f32_e32 v80, v64, v65
	v_max3_f32 v81, v66, v67, v49
	v_max3_f32 v80, v80, v48, v50
	v_max3_f32 v80, v80, v51, v68
	v_max3_f32 v81, v81, v70, v71
	v_max3_f32 v80, v80, v69, v52
	v_max3_f32 v81, v81, v54, v55
	v_max3_f32 v80, v80, v53, v72
	v_max3_f32 v81, v81, v74, v75
	v_max3_f32 v80, v80, v73, v56
	v_max3_f32 v81, v81, v58, v59
	v_max3_f32 v80, v80, v57, v76
	v_max3_f32 v81, v81, v78, v79
	v_max3_f32 v80, v80, v77, v60
	v_max3_f32 v81, v81, v62, v63
	v_max3_f32 v80, v80, v61, v81
	v_mov_b32_e32 v81, v80
	s_nop 1
	v_permlane32_swap_b32_e32 v80, v81
	v_max_f32_e32 v81, v81, v81
	v_max_f32_e32 v80, v80, v80
	v_max_f32_e32 v80, v80, v81
	v_cmp_lt_f32_e32 vcc, s61, v80
	s_cmp_lg_u64 vcc, 0
	v_add_f32_e32 v197, v231, v180
	s_cselect_b64 s[10:11], -1, 0
	s_cbranch_vccnz .LBB0_795
